# scan loop: dedicated landing registers for both load stages, loads issued behind each park (2 steps of prefetch slack), on top of prep fixes
# baseline (speedup 1.0000x reference)
; __device__ __forceinline__ void seq_item(const Params& p, unsigned char* shm, int row0, int nchunks, int h, const float* S0, float* Sout) {
;     ...
;     auto gload = [&](int ci, Stage& G) {
;         const size_t cb = (size_t)(chi0 + ci * 16) * 4096 + crow * 64 + cseg;
;         G.g[0] = *(const u32x4*)(p.W1G + cb); G.g[1] = *(const u32x4*)(p.BPG + cb); G.g[2] = *(const u32x4*)(p.U0G + cb); G.g[3] = *(const u32x4*)(p.VKG + cb);
;         G.gc = *(const f32x4*)(p.GCG + (size_t)(chi0 + ci * 16) * 64 + (tid & 15) * 4);
;     };
;     auto park = [&](int slot, const Stage& G) {
;         bf16_t* d = ring + slot * SLOT;
; #pragma unroll
;         for (int a = 0; a < 4; ++a) *(u32x4*)(d + a * 64 * LD + crow * LD + cseg) = G.g[a];
;         if (tid < 16) *(f32x4*)((float*)(d + 4 * 64 * LD) + tid * 4) = G.gc;
;     };
;     auto body = [&](int ci, int slot, int pslot, const Stage& G) {
;         const bf16_t* W1s = ring + slot * SLOT; const bf16_t* BPs = W1s + 64 * LD; const bf16_t* U0s = BPs + 64 * LD; const bf16_t* VKs = U0s + 64 * LD;
;         const float* GCs = (const float*)(VKs + 64 * LD);
;         const size_t cb = (size_t)(chi0 + ci * 16) * 4096;
; #pragma unroll
;         for (int q = 0; q < 2; ++q) *(u32x2*)(Sb + (16 * (nv0 + q) + fr) * LD + c0) = pk_bf4(S[q]);
;         LDS_BARRIER();
;         park(pslot, G);
;         *(u32x4*)(p.Z + (size_t)(row0 + ci * 64 + crow) * LDZ + ZC_S + h * 64 + cseg) = *(const u32x4*)(Sb + crow * LD + cseg);
;         const bf16x8 w10 = ldfrag(W1s, LD, 16 * m, 0, fr, fq), w11 = ldfrag(W1s, LD, 16 * m, 32, fr, fq);
; #pragma unroll
;         for (int q = 0; q < 2; ++q) {
;             const int v = 16 * (nv0 + q) + fr;
;             f32x4 acc = up_bf4(*(const u32x2*)(U0s + v * LD + c0));
;             acc = MFMA16(w10, ldfrag(Sb, LD, 16 * (nv0 + q), 0, fr, fq), acc);
;             acc = MFMA16(w11, ldfrag(Sb, LD, 16 * (nv0 + q), 32, fr, fq), acc);
;             *(u32x2*)(UT + v * LD + c0) = pk_bf4(acc);
;         }
;         LDS_BARRIER();
;         *(u32x4*)(p.UTG + cb + crow * 64 + cseg) = *(const u32x4*)(UT + crow * LD + cseg);
;         const bf16x8 bp0 = ldfrag(BPs, LD, 16 * m, 0, fr, fq), bp1 = ldfrag(BPs, LD, 16 * m, 32, fr, fq);
;         const f32x4 gc = *(const f32x4*)(GCs + c0);
; #pragma unroll
;         for (int q = 0; q < 2; ++q) {
;             const int v = 16 * (nv0 + q) + fr;
.LBB0_434:
	s_or_b64 exec, exec, s[4:5]
	s_add_i32 s4, 0, 0x12100
	s_waitcnt vmcnt(4)
	ds_write_b128 v60, v[4:7] offset:55552
	s_waitcnt vmcnt(3)
	ds_write_b128 v60, v[12:15] offset:64768
	v_add3_u32 v4, s4, v51, v48
	s_add_i32 s4, 0, 0x14500
	s_waitcnt vmcnt(2)
	ds_write_b128 v4, v[8:11]
	v_add3_u32 v4, s4, v51, v48
	s_waitcnt vmcnt(0)
	ds_write_b128 v4, v[16:19]
	s_and_saveexec_b64 s[4:5], s[8:9]
	v_add_u32_e32 v4, 0x16900, v23
	ds_write_b128 v4, v[0:3]
	s_or_b64 exec, exec, s[4:5]
	s_or_b32 s4, s6, 32
	s_ashr_i32 s5, s4, 31
	s_lshl_b64 s[24:25], s[4:5], 12
	v_lshl_add_u64 v[0:1], s[24:25], 0, v[20:21]
	v_or_b32_e32 v0, v0, v22
	s_lshl_b64 s[4:5], s[4:5], 8
	v_lshlrev_b64 v[12:13], 1, v[0:1]
	s_add_u32 s4, s10, s4
	v_lshl_add_u64 v[0:1], s[12:13], 0, v[12:13]
	v_lshl_add_u64 v[4:5], s[14:15], 0, v[12:13]
	v_lshl_add_u64 v[8:9], s[16:17], 0, v[12:13]
	v_lshl_add_u64 v[12:13], s[18:19], 0, v[12:13]
	s_addc_u32 s5, s11, s5
	global_load_dwordx4 v[220:223], v[0:1], off
	v_and_b32_e32 v61, 2, v169
	global_load_dwordx4 v[224:227], v[4:5], off
	v_or_b32_e32 v52, v20, v22
	global_load_dwordx4 v[228:231], v[8:9], off
	v_lshl_or_b32 v20, v61, 4, v161
	global_load_dwordx4 v[232:235], v[12:13], off
	v_bfe_u32 v21, v133, 4, 2
	global_load_dwordx4 v[236:239], v120, s[4:5]
	v_and_b32_e32 v23, 0x70, v164
	v_mul_u32_u24_e32 v62, 0x48, v20
	v_lshl_or_b32 v50, v21, 2, v23
	v_lshl_add_u32 v20, v62, 1, 0
	v_lshlrev_b32_e32 v22, 1, v50
	v_add_u32_e32 v24, 0x900, v20
	v_add_u32_e32 v63, v20, v22
	v_add_u32_e32 v64, v24, v22
	v_or_b32_e32 v22, v23, v161
	v_mov_b32_e32 v49, 0
	v_mul_u32_u24_e32 v65, 0x90, v22
	v_lshlrev_b32_e32 v22, 3, v21
	v_lshlrev_b32_e32 v21, 4, v21
	v_add_u32_e32 v66, v20, v21
	v_add_u32_e32 v67, v24, v21
	s_or_b32 s24, s6, 48
	s_or_b32 s25, s6, 64
	s_lshl_b64 s[6:7], s[6:7], 13
	v_and_b32_e32 v20, 0x3f80, v166
	v_mov_b32_e32 v21, v49
	v_lshl_add_u64 v[56:57], s[6:7], 0, v[20:21]
	s_add_i32 s6, s21, s20
	s_add_i32 s6, s6, 16
	s_ashr_i32 s7, s6, 31
	v_and_b32_e32 v23, 7, v133
	s_lshl_b64 s[6:7], s[6:7], 13
	s_mov_b32 s5, 0
	v_mov_b32_e32 v121, v49
	s_lshl_b32 s4, s20, 6
	v_lshlrev_b32_e32 v23, 4, v23
	v_lshl_add_u64 v[58:59], s[6:7], 0, v[20:21]
	s_mov_b32 s22, 2
	v_mov_b32_e32 v53, v49
	v_lshl_add_u64 v[54:55], s[10:11], 0, v[120:121]
	v_add_u32_e32 v68, s23, v164
	v_or_b32_e32 v56, v56, v23
	v_or_b32_e32 v58, v58, v23
	s_mov_b32 s26, -2
	s_movk_i32 s27, 0x3a00
	s_lshl_b32 s4, s4, 1
	s_mov_b64 s[6:7], 0x40000
	v_lshlrev_b32_e32 v69, 1, v22
	s_mov_b32 s28, s5
	v_mov_b32_e32 v20, v49
	v_mov_b32_e32 v22, v49
	v_mov_b32_e32 v23, v49
	v_mov_b32_e32 v24, v49
	v_mov_b32_e32 v25, v49
	v_mov_b32_e32 v26, v49
	v_mov_b32_e32 v27, v49
	s_mov_b32 s86, 0
	s_lshl_b32 s86, s86, 4
	s_add_i32 s86, s24, s86
	s_ashr_i32 s87, s86, 31
	s_lshl_b64 s[88:89], s[86:87], 12
	s_lshl_b64 s[86:87], s[86:87], 8
	v_lshl_add_u64 v[190:191], s[88:89], 0, v[52:53]
	v_lshlrev_b64 v[190:191], 1, v[190:191]
	v_lshl_add_u64 v[192:193], s[12:13], 0, v[190:191]
	global_load_dwordx4 v[200:203], v[192:193], off
	v_lshl_add_u64 v[194:195], s[14:15], 0, v[190:191]
	global_load_dwordx4 v[204:207], v[194:195], off
	v_lshl_add_u64 v[192:193], s[16:17], 0, v[190:191]
	global_load_dwordx4 v[208:211], v[192:193], off
	v_lshl_add_u64 v[194:195], s[18:19], 0, v[190:191]
	global_load_dwordx4 v[212:215], v[194:195], off
	v_lshl_add_u64 v[192:193], v[54:55], 0, s[86:87]
	global_load_dwordx4 v[216:219], v[192:193], off
	s_waitcnt vmcnt(0)
	s_branch .LBB0_438
.LBB0_437:
	s_or_b64 exec, exec, s[22:23]
	s_add_i32 s22, s28, 1
	s_cmp_lg_u32 s28, 2
	s_cselect_b32 s22, s22, 0
	s_mul_i32 s23, s22, 0x9100
	s_add_i32 s23, s23, 0
	v_add3_u32 v80, s23, v65, v69
	v_add3_u32 v81, s23, v70, v71
	ds_read_b64 v[38:39], v81 offset:36864
	s_nop 0
	ds_read_b128 v[28:31], v80 offset:18496
	ds_read_b128 v[32:35], v80 offset:18432
	ds_read_b128 v[40:43], v60
	ds_read_b128 v[44:47], v66
	ds_read_b128 v[70:73], v66 offset:64
	ds_read_b128 v[74:77], v67 offset:64
	s_waitcnt lgkmcnt(6)
	v_lshlrev_b32_e32 v36, 16, v38
	v_and_b32_e32 v37, 0xffff0000, v38
	v_lshlrev_b32_e32 v38, 16, v39
	v_and_b32_e32 v39, 0xffff0000, v39
	v_add_u32_e32 v82, 64, v68
	v_mov_b64_e32 v[78:79], s[20:21]
	s_waitcnt lgkmcnt(2)
	v_mfma_f32_16x16x32_bf16 v[36:39], v[32:35], v[44:47], v[36:39]
	ds_read_b128 v[44:47], v67
	v_mad_i64_i32 v[78:79], s[20:21], v82, s27, v[78:79]
	s_waitcnt lgkmcnt(2)
	v_mfma_f32_16x16x32_bf16 v[36:39], v[28:31], v[70:73], v[36:39]
	v_add_u32_e32 v68, 0x80, v68
	v_lshl_add_u64 v[56:57], v[56:57], 0, s[6:7]
	s_add_i32 s86, s26, 2
	s_min_u32 s86, s86, 0x7c
	s_lshl_b32 s86, s86, 4
	s_add_i32 s86, s24, s86
	s_ashr_i32 s87, s86, 31
	s_lshl_b64 s[88:89], s[86:87], 12
	s_lshl_b64 s[86:87], s[86:87], 8
	v_lshl_add_u64 v[190:191], s[88:89], 0, v[52:53]
	v_lshlrev_b64 v[190:191], 1, v[190:191]
	v_lshl_add_u64 v[192:193], s[12:13], 0, v[190:191]
	global_load_dwordx4 v[200:203], v[192:193], off
	v_lshl_add_u64 v[194:195], s[14:15], 0, v[190:191]
	global_load_dwordx4 v[204:207], v[194:195], off
	v_lshl_add_u64 v[192:193], s[16:17], 0, v[190:191]
	global_load_dwordx4 v[208:211], v[192:193], off
	v_lshl_add_u64 v[194:195], s[18:19], 0, v[190:191]
	global_load_dwordx4 v[212:215], v[194:195], off
	v_lshl_add_u64 v[192:193], v[54:55], 0, s[86:87]
	global_load_dwordx4 v[216:219], v[192:193], off
	s_nop 5
	v_cvt_pk_bf16_f32 v36, v36, v37
	v_cvt_pk_bf16_f32 v37, v38, v39
	ds_write_b64 v63, v[36:37] offset:9216
	ds_read_b64 v[38:39], v81 offset:39168
	v_lshl_add_u64 v[36:37], v[78:79], 0, s[4:5]
	v_lshl_add_u64 v[70:71], v[36:37], 0, v[48:49]
	v_add_co_u32_e32 v70, vcc, 0x1000, v70
	s_waitcnt lgkmcnt(0)
	v_lshlrev_b32_e32 v36, 16, v38
	v_and_b32_e32 v37, 0xffff0000, v38
	v_lshlrev_b32_e32 v38, 16, v39
	v_and_b32_e32 v39, 0xffff0000, v39
	v_addc_co_u32_e32 v71, vcc, 0, v71, vcc
	s_nop 0
	v_mfma_f32_16x16x32_bf16 v[32:35], v[32:35], v[44:47], v[36:39]
	global_store_dwordx4 v[70:71], v[40:43], off offset:2048
	v_mfma_f32_16x16x32_bf16 v[28:31], v[28:31], v[74:77], v[32:35]
	s_nop 0
	v_lshl_add_u32 v36, v50, 2, s23
	s_nop 5
	v_cvt_pk_bf16_f32 v28, v28, v29
	v_cvt_pk_bf16_f32 v29, v30, v31
	ds_write_b64 v64, v[28:29] offset:9216
	s_waitcnt lgkmcnt(0)
	s_barrier
; __device__ __forceinline__ void seq_item(const Params& p, unsigned char* shm, int row0, int nchunks, int h, const float* S0, float* Sout) {
;     ...
;     auto body = [&](int ci, int slot, int pslot, const Stage& G) {
;         const bf16_t* W1s = ring + slot * SLOT; const bf16_t* BPs = W1s + 64 * LD; const bf16_t* U0s = BPs + 64 * LD; const bf16_t* VKs = U0s + 64 * LD;
;         const float* GCs = (const float*)(VKs + 64 * LD);
;         const size_t cb = (size_t)(chi0 + ci * 16) * 4096;
; #pragma unroll
;         for (int q = 0; q < 2; ++q) *(u32x2*)(Sb + (16 * (nv0 + q) + fr) * LD + c0) = pk_bf4(S[q]);
;         LDS_BARRIER();
;         park(pslot, G);
;         *(u32x4*)(p.Z + (size_t)(row0 + ci * 64 + crow) * LDZ + ZC_S + h * 64 + cseg) = *(const u32x4*)(Sb + crow * LD + cseg);
;         const bf16x8 w10 = ldfrag(W1s, LD, 16 * m, 0, fr, fq), w11 = ldfrag(W1s, LD, 16 * m, 32, fr, fq);
; #pragma unroll
;         for (int q = 0; q < 2; ++q) {
;             const int v = 16 * (nv0 + q) + fr;
;             f32x4 acc = up_bf4(*(const u32x2*)(U0s + v * LD + c0));
;             acc = MFMA16(w10, ldfrag(Sb, LD, 16 * (nv0 + q), 0, fr, fq), acc);
;             acc = MFMA16(w11, ldfrag(Sb, LD, 16 * (nv0 + q), 32, fr, fq), acc);
;             *(u32x2*)(UT + v * LD + c0) = pk_bf4(acc);
;         }
;         LDS_BARRIER();
;         *(u32x4*)(p.UTG + cb + crow * 64 + cseg) = *(const u32x4*)(UT + crow * LD + cseg);
;         const bf16x8 bp0 = ldfrag(BPs, LD, 16 * m, 0, fr, fq), bp1 = ldfrag(BPs, LD, 16 * m, 32, fr, fq);
;         const f32x4 gc = *(const f32x4*)(GCs + c0);
; #pragma unroll
;         for (int q = 0; q < 2; ++q) {
;             const int v = 16 * (nv0 + q) + fr;
;             f32x4 acc = S[q] * gc + up_bf4(*(const u32x2*)(VKs + v * LD + c0));
;             acc = MFMA16(bp0, ldfrag(UT, LD, 16 * (nv0 + q), 0, fr, fq), acc);
;             acc = MFMA16(bp1, ldfrag(UT, LD, 16 * (nv0 + q), 32, fr, fq), acc);
;             S[q] = acc;
;         }
;     };
;     Stage A, B;
;     gload(0, A); gload(min(1, last), B);
;     park(0, A); park(1, B);
;     gload(min(2, last), A);
;     int scur = 0, spark = 2;
;     for (int ci = 0; ci < nchunks; ci += 2) {
;         gload(min(ci + 3, last), B);
;         body(ci, scur, spark, A);
;         scur = scur == 2 ? 0 : scur + 1; spark = spark == 2 ? 0 : spark + 1;
;         if (ci + 1 >= nchunks) break;
	ds_read_b64 v[40:41], v81 offset:46080
	ds_read_b128 v[28:31], v80 offset:27712
	ds_read_b128 v[32:35], v80 offset:27648
	ds_read_b128 v[36:39], v36 offset:55296
	s_waitcnt lgkmcnt(3)
	v_lshlrev_b32_e32 v44, 16, v40
	v_and_b32_e32 v45, 0xffff0000, v40
	v_lshlrev_b32_e32 v46, 16, v41
	v_and_b32_e32 v47, 0xffff0000, v41
	ds_read_b128 v[40:43], v66 offset:9216
	ds_read_b64 v[74:75], v81 offset:48384
	s_waitcnt lgkmcnt(2)
	v_pk_fma_f32 v[26:27], v[26:27], v[38:39], v[46:47]
	v_pk_fma_f32 v[24:25], v[24:25], v[36:37], v[44:45]
	ds_read_b128 v[44:47], v67 offset:9280
	s_waitcnt lgkmcnt(2)
	v_mfma_f32_16x16x32_bf16 v[24:27], v[32:35], v[40:43], v[24:27]
	ds_read_b128 v[40:43], v66 offset:9280
	ds_read_b128 v[70:73], v67 offset:9216
	s_waitcnt lgkmcnt(1)
	v_mfma_f32_16x16x32_bf16 v[24:27], v[28:31], v[40:43], v[24:27]
	v_lshlrev_b32_e32 v40, 16, v74
	v_and_b32_e32 v41, 0xffff0000, v74
	v_lshlrev_b32_e32 v42, 16, v75
	v_and_b32_e32 v43, 0xffff0000, v75
	v_pk_fma_f32 v[22:23], v[22:23], v[38:39], v[42:43]
	v_pk_fma_f32 v[20:21], v[20:21], v[36:37], v[40:41]
	v_lshl_add_u64 v[36:37], s[10:11], 0, v[58:59]
	s_add_i32 s10, s22, 1
	s_waitcnt lgkmcnt(0)
	v_mfma_f32_16x16x32_bf16 v[20:23], v[32:35], v[70:73], v[20:23]
	ds_read_b128 v[32:35], v60 offset:9216
	s_cmp_lg_u32 s22, 2
	s_cselect_b32 s28, s10, 0
	v_mfma_f32_16x16x32_bf16 v[20:23], v[28:31], v[44:47], v[20:23]
	s_add_i32 s10, s29, 1
	s_cmp_lg_u32 s29, 2
	s_cselect_b32 s22, s10, 0
	s_cmpk_lt_u32 s26, 0x7e
	v_lshl_add_u64 v[58:59], v[58:59], 0, s[6:7]
	s_waitcnt lgkmcnt(0)
	global_store_dwordx4 v[36:37], v[32:35], off
	s_cbranch_scc0 .LBB0_442
.LBB0_438:
	s_add_i32 s26, s26, 2
	s_min_u32 s10, s26, 0x7c
	s_lshl_b32 s10, s10, 4
	s_add_i32 s10, s24, s10
	s_ashr_i32 s11, s10, 31
	s_lshl_b64 s[20:21], s[10:11], 12
	v_lshl_add_u64 v[28:29], s[20:21], 0, v[52:53]
	v_lshlrev_b64 v[28:29], 1, v[28:29]
	v_lshl_add_u64 v[30:31], s[12:13], 0, v[28:29]
	s_nop 0
	v_lshl_add_u64 v[30:31], s[14:15], 0, v[28:29]
	s_nop 0
	v_lshl_add_u64 v[30:31], s[16:17], 0, v[28:29]
	v_lshl_add_u64 v[28:29], s[18:19], 0, v[28:29]
	s_lshl_b64 s[10:11], s[10:11], 8
	s_nop 0
	v_lshl_add_u64 v[28:29], v[54:55], 0, s[10:11]
	s_nop 0
	v_cvt_pk_bf16_f32 v70, v24, v25
	s_nop 0
	v_cvt_pk_bf16_f32 v71, v26, v27
	ds_write_b64 v63, v[70:71]
	v_cvt_pk_bf16_f32 v70, v20, v21
	v_cvt_pk_bf16_f32 v71, v22, v23
	ds_write_b64 v64, v[70:71]
	s_waitcnt lgkmcnt(0)
	s_barrier
	s_mul_i32 s10, s22, 0x9100
	s_add_i32 s20, s10, 0
	v_add3_u32 v70, s20, v51, v48
	s_waitcnt vmcnt(13)
	ds_write_b128 v70, v[220:223] offset:18432
	s_waitcnt vmcnt(12)
	ds_write_b128 v70, v[224:227] offset:27648
	s_waitcnt vmcnt(11)
	ds_write_b128 v70, v[228:231] offset:36864
	s_waitcnt vmcnt(10)
	ds_write_b128 v70, v[232:235] offset:46080
	s_and_saveexec_b64 s[10:11], s[8:9]
	s_cbranch_execz .LBB0_440
	v_lshl_add_u32 v0, v134, 2, s20
	s_waitcnt vmcnt(9)
	ds_write_b128 v0, v[236:239] offset:55296
; __device__ __forceinline__ void seq_item(const Params& p, unsigned char* shm, int row0, int nchunks, int h, const float* S0, float* Sout) {
;     ...
;     auto body = [&](int ci, int slot, int pslot, const Stage& G) {
;         const bf16_t* W1s = ring + slot * SLOT; const bf16_t* BPs = W1s + 64 * LD; const bf16_t* U0s = BPs + 64 * LD; const bf16_t* VKs = U0s + 64 * LD;
;         const float* GCs = (const float*)(VKs + 64 * LD);
;         const size_t cb = (size_t)(chi0 + ci * 16) * 4096;
; #pragma unroll
;         for (int q = 0; q < 2; ++q) *(u32x2*)(Sb + (16 * (nv0 + q) + fr) * LD + c0) = pk_bf4(S[q]);
;         LDS_BARRIER();
;         park(pslot, G);
;         *(u32x4*)(p.Z + (size_t)(row0 + ci * 64 + crow) * LDZ + ZC_S + h * 64 + cseg) = *(const u32x4*)(Sb + crow * LD + cseg);
;         const bf16x8 w10 = ldfrag(W1s, LD, 16 * m, 0, fr, fq), w11 = ldfrag(W1s, LD, 16 * m, 32, fr, fq);
; #pragma unroll
;         for (int q = 0; q < 2; ++q) {
;             const int v = 16 * (nv0 + q) + fr;
;             f32x4 acc = up_bf4(*(const u32x2*)(U0s + v * LD + c0));
;             acc = MFMA16(w10, ldfrag(Sb, LD, 16 * (nv0 + q), 0, fr, fq), acc);
;             acc = MFMA16(w11, ldfrag(Sb, LD, 16 * (nv0 + q), 32, fr, fq), acc);
;             *(u32x2*)(UT + v * LD + c0) = pk_bf4(acc);
;         }
;         LDS_BARRIER();
;         *(u32x4*)(p.UTG + cb + crow * 64 + cseg) = *(const u32x4*)(UT + crow * LD + cseg);
;         const bf16x8 bp0 = ldfrag(BPs, LD, 16 * m, 0, fr, fq), bp1 = ldfrag(BPs, LD, 16 * m, 32, fr, fq);
;         const f32x4 gc = *(const f32x4*)(GCs + c0);
; #pragma unroll
;         for (int q = 0; q < 2; ++q) {
;             const int v = 16 * (nv0 + q) + fr;
;             f32x4 acc = S[q] * gc + up_bf4(*(const u32x2*)(VKs + v * LD + c0));
;             acc = MFMA16(bp0, ldfrag(UT, LD, 16 * (nv0 + q), 0, fr, fq), acc);
;             acc = MFMA16(bp1, ldfrag(UT, LD, 16 * (nv0 + q), 32, fr, fq), acc);
;             S[q] = acc;
;         }
;     };
;     Stage A, B;
;     gload(0, A); gload(min(1, last), B);
;     park(0, A); park(1, B);
;     gload(min(2, last), A);
;     int scur = 0, spark = 2;
;     for (int ci = 0; ci < nchunks; ci += 2) {
;         gload(min(ci + 3, last), B);
;         body(ci, scur, spark, A);
;         scur = scur == 2 ? 0 : scur + 1; spark = spark == 2 ? 0 : spark + 1;
;         if (ci + 1 >= nchunks) break;
.LBB0_440:
	s_or_b64 exec, exec, s[10:11]
	s_mul_i32 s10, s28, 0x9100
	s_add_i32 s34, s10, 0
	v_lshlrev_b32_e32 v70, 1, v62
	v_lshlrev_b32_e32 v71, 1, v50
	v_add3_u32 v90, s34, v70, v71
	ds_read_b64 v[10:11], v90 offset:36864
	v_add3_u32 v80, s34, v65, v69
	s_load_dwordx2 s[20:21], s[0:1], 0xb8
	ds_read_b128 v[0:3], v80 offset:18432
	ds_read_b128 v[4:7], v80 offset:18496
	ds_read_b128 v[12:15], v60
	s_nop 0
	ds_read_b128 v[16:19], v66
	s_waitcnt lgkmcnt(0)
	v_lshlrev_b32_e32 v8, 16, v10
	v_and_b32_e32 v9, 0xffff0000, v10
	v_lshlrev_b32_e32 v10, 16, v11
	v_and_b32_e32 v11, 0xffff0000, v11
	ds_read_b128 v[72:75], v66 offset:64
	v_mov_b64_e32 v[76:77], s[20:21]
	v_mfma_f32_16x16x32_bf16 v[8:11], v[0:3], v[16:19], v[8:11]
	ds_read_b128 v[16:19], v67
	v_mad_i64_i32 v[76:77], s[10:11], v68, s27, v[76:77]
	s_waitcnt lgkmcnt(1)
	v_mfma_f32_16x16x32_bf16 v[8:11], v[4:7], v[72:75], v[8:11]
	s_add_i32 s23, s22, 1
	s_cmp_lg_u32 s22, 2
	s_cselect_b32 s29, s23, 0
	s_min_u32 s22, s26, 0x7b
	s_lshl_b32 s22, s22, 4
	s_min_u32 s86, s26, 0x7b
	s_lshl_b32 s86, s86, 4
	s_add_i32 s86, s25, s86
	s_ashr_i32 s87, s86, 31
	s_lshl_b64 s[88:89], s[86:87], 12
	s_lshl_b64 s[86:87], s[86:87], 8
	v_lshl_add_u64 v[190:191], s[88:89], 0, v[52:53]
	v_lshlrev_b64 v[190:191], 1, v[190:191]
	v_lshl_add_u64 v[192:193], s[12:13], 0, v[190:191]
	global_load_dwordx4 v[220:223], v[192:193], off
	v_lshl_add_u64 v[194:195], s[14:15], 0, v[190:191]
	global_load_dwordx4 v[224:227], v[194:195], off
	v_lshl_add_u64 v[192:193], s[16:17], 0, v[190:191]
	global_load_dwordx4 v[228:231], v[192:193], off
	v_lshl_add_u64 v[194:195], s[18:19], 0, v[190:191]
	global_load_dwordx4 v[232:235], v[194:195], off
	v_lshl_add_u64 v[192:193], v[54:55], 0, s[86:87]
	global_load_dwordx4 v[236:239], v[192:193], off
	s_nop 2
	v_cvt_pk_bf16_f32 v8, v8, v9
	v_cvt_pk_bf16_f32 v9, v10, v11
	ds_write_b64 v63, v[8:9] offset:9216
	ds_read_b64 v[10:11], v90 offset:39168
	v_lshl_add_u64 v[8:9], v[76:77], 0, s[4:5]
	v_lshl_add_u64 v[72:73], v[8:9], 0, v[48:49]
	v_add_co_u32_e32 v72, vcc, 0x1000, v72
	s_waitcnt lgkmcnt(0)
	v_lshlrev_b32_e32 v8, 16, v10
	v_and_b32_e32 v9, 0xffff0000, v10
	v_lshlrev_b32_e32 v10, 16, v11
	v_and_b32_e32 v11, 0xffff0000, v11
	v_addc_co_u32_e32 v73, vcc, 0, v73, vcc
	s_nop 0
	v_mfma_f32_16x16x32_bf16 v[0:3], v[0:3], v[16:19], v[8:11]
	global_store_dwordx4 v[72:73], v[12:15], off offset:2048
	s_add_i32 s22, s25, s22
	s_ashr_i32 s23, s22, 31
	ds_read_b128 v[8:11], v67 offset:64
	s_waitcnt lgkmcnt(0)
	v_mfma_f32_16x16x32_bf16 v[0:3], v[4:7], v[8:11], v[0:3]
	s_lshl_b64 s[30:31], s[22:23], 12
	s_lshl_b64 s[22:23], s[22:23], 8
	v_lshl_add_u64 v[16:17], v[54:55], 0, s[22:23]
	s_nop 4
	v_cvt_pk_bf16_f32 v0, v0, v1
	v_cvt_pk_bf16_f32 v1, v2, v3
	ds_write_b64 v64, v[0:1] offset:9216
	s_waitcnt lgkmcnt(0)
	s_barrier
	s_load_dwordx2 s[10:11], s[0:1], 0x100
	ds_read_b128 v[0:3], v60 offset:9216
	ds_read_b128 v[72:75], v66 offset:9216
	v_lshl_add_u32 v84, v50, 2, s34
	s_mul_i32 s22, s29, 0x9100
	s_waitcnt lgkmcnt(0)
	v_lshl_add_u64 v[4:5], s[10:11], 0, v[56:57]
	global_store_dwordx4 v[4:5], v[0:3], off
	s_nop 0
	s_nop 0
	v_lshl_add_u64 v[0:1], s[30:31], 0, v[52:53]
	v_lshlrev_b64 v[12:13], 1, v[0:1]
	v_lshl_add_u64 v[0:1], s[12:13], 0, v[12:13]
	v_lshl_add_u64 v[4:5], s[14:15], 0, v[12:13]
	v_lshl_add_u64 v[8:9], s[16:17], 0, v[12:13]
	v_lshl_add_u64 v[12:13], s[18:19], 0, v[12:13]
	s_nop 0
	s_add_i32 s30, s22, 0
	s_nop 0
	s_nop 0
	s_nop 0
	s_nop 0
	s_nop 0
	ds_read_b64 v[88:89], v90 offset:46080
	ds_read_b128 v[76:79], v80 offset:27648
	ds_read_b128 v[80:83], v80 offset:27712
	ds_read_b128 v[84:87], v84 offset:55296
	ds_read_b64 v[92:93], v90 offset:48384
	s_waitcnt lgkmcnt(4)
	v_lshlrev_b32_e32 v90, 16, v88
	v_and_b32_e32 v91, 0xffff0000, v88
	v_lshlrev_b32_e32 v88, 16, v89
	v_and_b32_e32 v89, 0xffff0000, v89
	s_waitcnt lgkmcnt(1)
	v_pk_fma_f32 v[26:27], v[26:27], v[86:87], v[88:89]
	v_pk_fma_f32 v[24:25], v[24:25], v[84:85], v[90:91]
	s_nop 1
	v_mfma_f32_16x16x32_bf16 v[24:27], v[76:79], v[72:75], v[24:27]
	ds_read_b128 v[72:75], v66 offset:9280
	ds_read_b128 v[88:91], v67 offset:9216
	s_waitcnt lgkmcnt(1)
	v_mfma_f32_16x16x32_bf16 v[24:27], v[80:83], v[72:75], v[24:27]
	v_lshlrev_b32_e32 v72, 16, v92
	v_and_b32_e32 v73, 0xffff0000, v92
	v_lshlrev_b32_e32 v74, 16, v93
	v_and_b32_e32 v75, 0xffff0000, v93
	v_pk_fma_f32 v[22:23], v[22:23], v[86:87], v[74:75]
	v_pk_fma_f32 v[20:21], v[20:21], v[84:85], v[72:73]
	ds_read_b128 v[72:75], v67 offset:9280
	s_waitcnt lgkmcnt(1)
	v_mfma_f32_16x16x32_bf16 v[20:23], v[76:79], v[88:91], v[20:23]
	s_waitcnt lgkmcnt(0)
	v_mfma_f32_16x16x32_bf16 v[20:23], v[80:83], v[72:75], v[20:23]
	v_cvt_pk_bf16_f32 v72, v24, v25
	v_cvt_pk_bf16_f32 v73, v26, v27
	ds_write_b64 v63, v[72:73]
	s_nop 4
	v_cvt_pk_bf16_f32 v72, v20, v21
	v_cvt_pk_bf16_f32 v73, v22, v23
	ds_write_b64 v64, v[72:73]
	s_waitcnt lgkmcnt(0)
	s_barrier
	v_add3_u32 v72, s30, v51, v48
	s_waitcnt vmcnt(13)
	ds_write_b128 v72, v[200:203] offset:18432
	s_waitcnt vmcnt(12)
	ds_write_b128 v72, v[204:207] offset:27648
	s_waitcnt vmcnt(10)
	ds_write_b128 v72, v[208:211] offset:36864
	ds_write_b128 v72, v[212:215] offset:46080
	s_and_saveexec_b64 s[22:23], s[8:9]
	s_cbranch_execz .LBB0_437
	v_lshl_add_u32 v32, v134, 2, s30
	s_waitcnt vmcnt(9)
	ds_write_b128 v32, v[216:219] offset:55296
	s_branch .LBB0_437
